# G1 K-loop header: compiler's vmcnt(0) replaced by the counted vmcnt(8) the pipeline was designed for (8 DMA loads stay in flight across the back edge)
# baseline (speedup 1.0000x reference)
; #define PG8_STAGE(bufoff, gbase, voff) do { _Pragma("unroll") for (int _i = 0; _i < 2; ++_i) \
;         __builtin_amdgcn_global_load_lds((const unsigned*)((const char*)(gbase) + (voff)[_i]), (PG8_LAS unsigned*)(lds + (bufoff) + ldsw + _i * 8192), 16, 0, 0); } while (0)
; #define PG8_LDA(dst, b, h) do { _Pragma("unroll") for (int m = 0; m < 4; ++m) _Pragma("unroll") for (int k = 0; k < 2; ++k) dst[m][k] = *(const PG8_LAS bf16x8*)(lds + PG8_SA(b, h) + aoff + m * 2048 + k * 1024); } while (0)
; #define PG8_LDB(dst, b, h) do { _Pragma("unroll") for (int n = 0; n < 2; ++n) _Pragma("unroll") for (int k = 0; k < 2; ++k) dst[n][k] = *(const PG8_LAS bf16x8*)(lds + PG8_SB(b, h) + boff + n * 2048 + k * 1024); } while (0)
; #define PG8_MMA(ai, bj, At, Bt) do { __builtin_amdgcn_s_setprio(1); _Pragma("unroll") for (int m = 0; m < 4; ++m) _Pragma("unroll") for (int n = 0; n < 2; ++n) _Pragma("unroll") for (int k = 0; k < 2; ++k) \
;         acc[ai][bj][m][n] = __builtin_amdgcn_mfma_f32_16x16x32_bf16(Bt[n][k], At[m][k], acc[ai][bj][m][n], 0, 0, 0); __builtin_amdgcn_s_setprio(0); } while (0)
; #define PG8_WAIT_V(n) asm volatile("s_waitcnt vmcnt(" #n ")" ::: "memory")
; #define PG8_WAIT_L(n) asm volatile("s_waitcnt lgkmcnt(" #n ")" ::: "memory")
; #define PG8_BAR __builtin_amdgcn_s_barrier()
; #define PG8_SCHED __builtin_amdgcn_sched_barrier(0)
; template <class Epi, class Sched, bool ALIGN_EPI = false, bool SP2 = false>
; __device__ __forceinline__ void gemm_phase(PG8_LAS unsigned char* lds, const Gemm g, const Sched& S, const Epi& E, const int tid_in) {
;     ...
;             const bool last = (t == nt - 2);
;             const char* a1 = cA + (size_t)(t + 1) * kstep;
;             const char* a2 = last ? nA : cA + (size_t)(t + 2) * kstep; const char* b2 = last ? nB : cB + (size_t)(t + 2) * kstep;
;             const char* a3 = a2 + kstep; const char* b3 = b2 + kstep;
;             if (last && has_next) S.a_ready(nxt);
;             if constexpr (SP2) {
;             PG8_LDB(B0, 0, 0); PG8_LDB(B1, 0, 1); PG8_SCHED; PG8_LDA(At, 0, 0); PG8_STAGE(PG8_SA(1, 1), a1 + hstep, voffA);
;             PG8_WAIT_V(8); PG8_WAIT_L(0); PG8_BAR; PG8_MMA(0, 0, At, B0); PG8_MMA(0, 1, At, B1); PG8_BAR; PG8_SCHED;
;             PG8_LDA(At, 0, 1); PG8_STAGE(PG8_SB(0, 0), b2, voffB); PG8_STAGE(PG8_SB(0, 1), b2 + hstep, voffB); PG8_STAGE(PG8_SA(0, 0), a2, voffA);
.LBB0_593:
	s_add_u32 s8, s42, 0xfff80080
	s_addc_u32 s9, s43, -1
	s_add_i32 s61, 0, 0x10000
	s_cmp_eq_u32 s57, 28
	s_cselect_b32 s11, s12, s9
	s_cselect_b32 s10, s13, s8
	s_cselect_b32 s9, s41, s55
	s_cselect_b32 s8, s44, s45
	s_add_i32 s64, 0, 0x14000
	s_waitcnt vmcnt(8)
	v_add_u32_e32 v92, s61, v196
	v_add_u32_e32 v96, s64, v196
	ds_read_b128 v[64:67], v92
	ds_read_b128 v[68:71], v92 offset:1024
	ds_read_b128 v[88:91], v92 offset:2048
	ds_read_b128 v[92:95], v92 offset:3072
	ds_read_b128 v[106:109], v96
	ds_read_b128 v[110:113], v96 offset:1024
	ds_read_b128 v[130:133], v96 offset:2048
	ds_read_b128 v[134:137], v96 offset:3072
	v_lshl_add_u64 v[180:181], s[42:43], 0, v[172:173]
	s_add_i32 m0, s20, 0xc000
	ds_read_b128 v[176:179], v198
	ds_read_b128 v[200:203], v198 offset:1024
	ds_read_b128 v[204:207], v198 offset:2048
	ds_read_b128 v[208:211], v198 offset:3072
	ds_read_b128 v[212:215], v198 offset:4096
	ds_read_b128 v[216:219], v198 offset:5120
	ds_read_b128 v[220:223], v198 offset:6144
	ds_read_b128 v[242:245], v198 offset:7168
	global_load_lds_dwordx4 v[180:181], off
	v_lshl_add_u64 v[180:181], s[42:43], 0, v[174:175]
	s_add_i32 m0, s20, 0xe000
	s_nop 0
	global_load_lds_dwordx4 v[180:181], off
	s_waitcnt vmcnt(8)
	s_waitcnt lgkmcnt(0)
	s_barrier
	s_setprio 1
	s_waitcnt lgkmcnt(0)
	v_mfma_f32_16x16x32_bf16 v[158:161], v[64:67], v[176:179], v[158:161]
	v_mfma_f32_16x16x32_bf16 v[154:157], v[88:91], v[176:179], v[154:157]
	v_mfma_f32_16x16x32_bf16 v[142:145], v[64:67], v[204:207], v[142:145]
	v_mfma_f32_16x16x32_bf16 v[138:141], v[88:91], v[204:207], v[138:141]
	v_mfma_f32_16x16x32_bf16 v[118:121], v[64:67], v[212:215], v[118:121]
	v_mfma_f32_16x16x32_bf16 v[114:117], v[88:91], v[212:215], v[114:117]
	v_mfma_f32_16x16x32_bf16 v[84:87], v[64:67], v[220:223], v[84:87]
	v_mfma_f32_16x16x32_bf16 v[80:83], v[88:91], v[220:223], v[80:83]
	v_mfma_f32_16x16x32_bf16 v[158:161], v[68:71], v[200:203], v[158:161]
	v_mfma_f32_16x16x32_bf16 v[154:157], v[92:95], v[200:203], v[154:157]
	v_mfma_f32_16x16x32_bf16 v[142:145], v[68:71], v[208:211], v[142:145]
	v_mfma_f32_16x16x32_bf16 v[138:141], v[92:95], v[208:211], v[138:141]
	v_mfma_f32_16x16x32_bf16 v[118:121], v[68:71], v[216:219], v[118:121]
	v_mfma_f32_16x16x32_bf16 v[114:117], v[92:95], v[216:219], v[114:117]
	v_mfma_f32_16x16x32_bf16 v[84:87], v[68:71], v[242:245], v[84:87]
	v_mfma_f32_16x16x32_bf16 v[80:83], v[92:95], v[242:245], v[80:83]
	s_setprio 0
	s_setprio 1
	v_mfma_f32_16x16x32_bf16 v[150:153], v[106:109], v[176:179], v[150:153]
	v_mfma_f32_16x16x32_bf16 v[146:149], v[130:133], v[176:179], v[146:149]
	v_mfma_f32_16x16x32_bf16 v[126:129], v[106:109], v[204:207], v[126:129]
	v_mfma_f32_16x16x32_bf16 v[122:125], v[130:133], v[204:207], v[122:125]
	v_mfma_f32_16x16x32_bf16 v[102:105], v[106:109], v[212:215], v[102:105]
	v_mfma_f32_16x16x32_bf16 v[98:101], v[130:133], v[212:215], v[98:101]
	v_mfma_f32_16x16x32_bf16 v[76:79], v[106:109], v[220:223], v[76:79]
	v_mfma_f32_16x16x32_bf16 v[72:75], v[130:133], v[220:223], v[72:75]
	v_mfma_f32_16x16x32_bf16 v[150:153], v[110:113], v[200:203], v[150:153]
	v_mfma_f32_16x16x32_bf16 v[146:149], v[134:137], v[200:203], v[146:149]
	v_mfma_f32_16x16x32_bf16 v[126:129], v[110:113], v[208:211], v[126:129]
	v_mfma_f32_16x16x32_bf16 v[122:125], v[134:137], v[208:211], v[122:125]
	v_mfma_f32_16x16x32_bf16 v[102:105], v[110:113], v[216:219], v[102:105]
	v_mfma_f32_16x16x32_bf16 v[98:101], v[134:137], v[216:219], v[98:101]
	v_mfma_f32_16x16x32_bf16 v[76:79], v[110:113], v[242:245], v[76:79]
	v_mfma_f32_16x16x32_bf16 v[72:75], v[134:137], v[242:245], v[72:75]
	s_setprio 0
	s_barrier
	s_add_i32 s61, s61, s19
	v_lshl_add_u64 v[180:181], s[8:9], 0, v[164:165]
	s_mov_b32 m0, s61
	ds_read_b128 v[176:179], v198 offset:16384
	ds_read_b128 v[200:203], v198 offset:17408
	ds_read_b128 v[204:207], v198 offset:18432
	ds_read_b128 v[208:211], v198 offset:19456
	ds_read_b128 v[212:215], v198 offset:20480
	ds_read_b128 v[216:219], v198 offset:21504
	ds_read_b128 v[220:223], v198 offset:22528
	ds_read_b128 v[242:245], v198 offset:23552
	global_load_lds_dwordx4 v[180:181], off
	s_add_i32 m0, s61, 0x2000
	s_add_u32 s62, s8, 0x80000
	v_lshl_add_u64 v[184:185], s[8:9], 0, v[168:169]
	s_addc_u32 s63, s9, 0
	s_add_i32 s61, s64, s19
	global_load_lds_dwordx4 v[184:185], off
	v_lshl_add_u64 v[186:187], s[62:63], 0, v[164:165]
	s_mov_b32 m0, s61
	v_lshl_add_u64 v[224:225], s[10:11], 0, v[166:167]
	global_load_lds_dwordx4 v[186:187], off
	v_lshl_add_u64 v[186:187], s[62:63], 0, v[168:169]
	s_add_i32 m0, s61, 0x2000
	s_nop 0
	global_load_lds_dwordx4 v[186:187], off
	v_lshl_add_u64 v[186:187], s[10:11], 0, v[162:163]
	s_mov_b32 m0, s20
	s_nop 0
	global_load_lds_dwordx4 v[186:187], off
	s_mov_b32 m0, s22
	s_nop 0
	global_load_lds_dwordx4 v[224:225], off
	s_waitcnt vmcnt(8)
	s_waitcnt lgkmcnt(0)
	s_barrier
; #define PG8_STAGE(bufoff, gbase, voff) do { _Pragma("unroll") for (int _i = 0; _i < 2; ++_i) \
;         __builtin_amdgcn_global_load_lds((const unsigned*)((const char*)(gbase) + (voff)[_i]), (PG8_LAS unsigned*)(lds + (bufoff) + ldsw + _i * 8192), 16, 0, 0); } while (0)
; #define PG8_LDA(dst, b, h) do { _Pragma("unroll") for (int m = 0; m < 4; ++m) _Pragma("unroll") for (int k = 0; k < 2; ++k) dst[m][k] = *(const PG8_LAS bf16x8*)(lds + PG8_SA(b, h) + aoff + m * 2048 + k * 1024); } while (0)
; #define PG8_LDB(dst, b, h) do { _Pragma("unroll") for (int n = 0; n < 2; ++n) _Pragma("unroll") for (int k = 0; k < 2; ++k) dst[n][k] = *(const PG8_LAS bf16x8*)(lds + PG8_SB(b, h) + boff + n * 2048 + k * 1024); } while (0)
; #define PG8_MMA(ai, bj, At, Bt) do { __builtin_amdgcn_s_setprio(1); _Pragma("unroll") for (int m = 0; m < 4; ++m) _Pragma("unroll") for (int n = 0; n < 2; ++n) _Pragma("unroll") for (int k = 0; k < 2; ++k) \
;         acc[ai][bj][m][n] = __builtin_amdgcn_mfma_f32_16x16x32_bf16(Bt[n][k], At[m][k], acc[ai][bj][m][n], 0, 0, 0); __builtin_amdgcn_s_setprio(0); } while (0)
; #define PG8_WAIT_V(n) asm volatile("s_waitcnt vmcnt(" #n ")" ::: "memory")
; #define PG8_WAIT_L(n) asm volatile("s_waitcnt lgkmcnt(" #n ")" ::: "memory")
; #define PG8_BAR __builtin_amdgcn_s_barrier()
; #define PG8_SCHED __builtin_amdgcn_sched_barrier(0)
; template <class Epi, class Sched, bool ALIGN_EPI = false, bool SP2 = false>
; __device__ __forceinline__ void gemm_phase(PG8_LAS unsigned char* lds, const Gemm g, const Sched& S, const Epi& E, const int tid_in) {
;     ...
;             PG8_WAIT_V(8); PG8_WAIT_L(0); PG8_BAR; PG8_MMA(1, 0, At, B0); PG8_MMA(1, 1, At, B1); PG8_BAR; PG8_SCHED;
;             PG8_LDB(B0, 1, 0); PG8_LDB(B1, 1, 1); PG8_SCHED; PG8_LDA(At, 1, 0); PG8_STAGE(PG8_SA(0, 1), a2 + hstep, voffA);
;             PG8_WAIT_V(8); PG8_WAIT_L(0); PG8_BAR; PG8_MMA(0, 0, At, B0); PG8_MMA(0, 1, At, B1); PG8_BAR; PG8_SCHED;
	s_setprio 1
	s_waitcnt lgkmcnt(0)
	v_mfma_f32_16x16x32_bf16 v[60:63], v[64:67], v[176:179], v[60:63]
	v_mfma_f32_16x16x32_bf16 v[56:59], v[88:91], v[176:179], v[56:59]
	v_mfma_f32_16x16x32_bf16 v[44:47], v[64:67], v[204:207], v[44:47]
	v_mfma_f32_16x16x32_bf16 v[40:43], v[88:91], v[204:207], v[40:43]
	v_mfma_f32_16x16x32_bf16 v[28:31], v[64:67], v[212:215], v[28:31]
	v_mfma_f32_16x16x32_bf16 v[24:27], v[88:91], v[212:215], v[24:27]
	v_mfma_f32_16x16x32_bf16 v[12:15], v[64:67], v[220:223], v[12:15]
	v_mfma_f32_16x16x32_bf16 v[8:11], v[88:91], v[220:223], v[8:11]
	v_mfma_f32_16x16x32_bf16 v[60:63], v[68:71], v[200:203], v[60:63]
	v_mfma_f32_16x16x32_bf16 v[56:59], v[92:95], v[200:203], v[56:59]
	v_mfma_f32_16x16x32_bf16 v[44:47], v[68:71], v[208:211], v[44:47]
	v_mfma_f32_16x16x32_bf16 v[40:43], v[92:95], v[208:211], v[40:43]
	v_mfma_f32_16x16x32_bf16 v[28:31], v[68:71], v[216:219], v[28:31]
	v_mfma_f32_16x16x32_bf16 v[24:27], v[92:95], v[216:219], v[24:27]
	v_mfma_f32_16x16x32_bf16 v[12:15], v[68:71], v[242:245], v[12:15]
	v_mfma_f32_16x16x32_bf16 v[8:11], v[92:95], v[242:245], v[8:11]
	s_setprio 0
	s_setprio 1
	v_mfma_f32_16x16x32_bf16 v[52:55], v[106:109], v[176:179], v[52:55]
	v_mfma_f32_16x16x32_bf16 v[48:51], v[130:133], v[176:179], v[48:51]
	v_mfma_f32_16x16x32_bf16 v[36:39], v[106:109], v[204:207], v[36:39]
	v_mfma_f32_16x16x32_bf16 v[32:35], v[130:133], v[204:207], v[32:35]
	v_mfma_f32_16x16x32_bf16 v[20:23], v[106:109], v[212:215], v[20:23]
	v_mfma_f32_16x16x32_bf16 v[16:19], v[130:133], v[212:215], v[16:19]
	v_mfma_f32_16x16x32_bf16 v[4:7], v[106:109], v[220:223], v[4:7]
	v_mfma_f32_16x16x32_bf16 v[0:3], v[130:133], v[220:223], v[0:3]
	v_mfma_f32_16x16x32_bf16 v[52:55], v[110:113], v[200:203], v[52:55]
	v_mfma_f32_16x16x32_bf16 v[48:51], v[134:137], v[200:203], v[48:51]
	v_mfma_f32_16x16x32_bf16 v[36:39], v[110:113], v[208:211], v[36:39]
	v_mfma_f32_16x16x32_bf16 v[32:35], v[134:137], v[208:211], v[32:35]
	v_mfma_f32_16x16x32_bf16 v[20:23], v[110:113], v[216:219], v[20:23]
	v_mfma_f32_16x16x32_bf16 v[16:19], v[134:137], v[216:219], v[16:19]
	v_mfma_f32_16x16x32_bf16 v[4:7], v[110:113], v[242:245], v[4:7]
	v_mfma_f32_16x16x32_bf16 v[0:3], v[134:137], v[242:245], v[0:3]
	s_setprio 0
	s_barrier
	s_add_i32 s61, 0, 0x18000
	s_add_i32 s62, 0, 0x1c000
	v_add_u32_e32 v92, s61, v196
	v_add_u32_e32 v96, s62, v196
	ds_read_b128 v[64:67], v92
	ds_read_b128 v[68:71], v92 offset:1024
	ds_read_b128 v[88:91], v92 offset:2048
	ds_read_b128 v[92:95], v92 offset:3072
	ds_read_b128 v[106:109], v96
	ds_read_b128 v[110:113], v96 offset:1024
	ds_read_b128 v[130:133], v96 offset:2048
	ds_read_b128 v[134:137], v96 offset:3072
	s_add_u32 s10, s10, 0x80000
	s_addc_u32 s11, s11, 0
	s_mov_b32 m0, s23
	v_lshl_add_u64 v[250:251], s[10:11], 0, v[162:163]
	ds_read_b128 v[176:179], v198 offset:32768
	ds_read_b128 v[200:203], v198 offset:33792
	ds_read_b128 v[204:207], v198 offset:34816
	ds_read_b128 v[208:211], v198 offset:35840
	ds_read_b128 v[212:215], v198 offset:36864
	ds_read_b128 v[216:219], v198 offset:37888
	ds_read_b128 v[220:223], v198 offset:38912
	ds_read_b128 v[242:245], v198 offset:39936
	global_load_lds_dwordx4 v[250:251], off
	v_lshl_add_u64 v[250:251], s[10:11], 0, v[166:167]
	s_mov_b32 m0, s34
	s_nop 0
	global_load_lds_dwordx4 v[250:251], off
	s_waitcnt vmcnt(8)
	s_waitcnt lgkmcnt(0)
	s_barrier
	s_setprio 1
	s_waitcnt lgkmcnt(0)
	v_mfma_f32_16x16x32_bf16 v[158:161], v[64:67], v[176:179], v[158:161]
	v_mfma_f32_16x16x32_bf16 v[154:157], v[88:91], v[176:179], v[154:157]
	v_mfma_f32_16x16x32_bf16 v[142:145], v[64:67], v[204:207], v[142:145]
	v_mfma_f32_16x16x32_bf16 v[138:141], v[88:91], v[204:207], v[138:141]
	v_mfma_f32_16x16x32_bf16 v[118:121], v[64:67], v[212:215], v[118:121]
	v_mfma_f32_16x16x32_bf16 v[114:117], v[88:91], v[212:215], v[114:117]
	v_mfma_f32_16x16x32_bf16 v[84:87], v[64:67], v[220:223], v[84:87]
	v_mfma_f32_16x16x32_bf16 v[80:83], v[88:91], v[220:223], v[80:83]
	v_mfma_f32_16x16x32_bf16 v[158:161], v[68:71], v[200:203], v[158:161]
	v_mfma_f32_16x16x32_bf16 v[154:157], v[92:95], v[200:203], v[154:157]
	v_mfma_f32_16x16x32_bf16 v[142:145], v[68:71], v[208:211], v[142:145]
	v_mfma_f32_16x16x32_bf16 v[138:141], v[92:95], v[208:211], v[138:141]
	v_mfma_f32_16x16x32_bf16 v[118:121], v[68:71], v[216:219], v[118:121]
	v_mfma_f32_16x16x32_bf16 v[114:117], v[92:95], v[216:219], v[114:117]
	v_mfma_f32_16x16x32_bf16 v[84:87], v[68:71], v[242:245], v[84:87]
	v_mfma_f32_16x16x32_bf16 v[80:83], v[92:95], v[242:245], v[80:83]
	s_setprio 0
	s_setprio 1
	v_mfma_f32_16x16x32_bf16 v[150:153], v[106:109], v[176:179], v[150:153]
	v_mfma_f32_16x16x32_bf16 v[146:149], v[130:133], v[176:179], v[146:149]
	v_mfma_f32_16x16x32_bf16 v[126:129], v[106:109], v[204:207], v[126:129]
	v_mfma_f32_16x16x32_bf16 v[122:125], v[130:133], v[204:207], v[122:125]
	v_mfma_f32_16x16x32_bf16 v[102:105], v[106:109], v[212:215], v[102:105]
	v_mfma_f32_16x16x32_bf16 v[98:101], v[130:133], v[212:215], v[98:101]
	v_mfma_f32_16x16x32_bf16 v[76:79], v[106:109], v[220:223], v[76:79]
	v_mfma_f32_16x16x32_bf16 v[72:75], v[130:133], v[220:223], v[72:75]
	v_mfma_f32_16x16x32_bf16 v[150:153], v[110:113], v[200:203], v[150:153]
	v_mfma_f32_16x16x32_bf16 v[146:149], v[134:137], v[200:203], v[146:149]
	v_mfma_f32_16x16x32_bf16 v[126:129], v[110:113], v[208:211], v[126:129]
	v_mfma_f32_16x16x32_bf16 v[122:125], v[134:137], v[208:211], v[122:125]
	v_mfma_f32_16x16x32_bf16 v[102:105], v[110:113], v[216:219], v[102:105]
	v_mfma_f32_16x16x32_bf16 v[98:101], v[134:137], v[216:219], v[98:101]
	v_mfma_f32_16x16x32_bf16 v[76:79], v[110:113], v[242:245], v[76:79]
	v_mfma_f32_16x16x32_bf16 v[72:75], v[134:137], v[242:245], v[72:75]
	s_setprio 0
	s_barrier
; #define PG8_STAGE(bufoff, gbase, voff) do { _Pragma("unroll") for (int _i = 0; _i < 2; ++_i) \
;         __builtin_amdgcn_global_load_lds((const unsigned*)((const char*)(gbase) + (voff)[_i]), (PG8_LAS unsigned*)(lds + (bufoff) + ldsw + _i * 8192), 16, 0, 0); } while (0)
; #define PG8_LDA(dst, b, h) do { _Pragma("unroll") for (int m = 0; m < 4; ++m) _Pragma("unroll") for (int k = 0; k < 2; ++k) dst[m][k] = *(const PG8_LAS bf16x8*)(lds + PG8_SA(b, h) + aoff + m * 2048 + k * 1024); } while (0)
; #define PG8_WAIT_V(n) asm volatile("s_waitcnt vmcnt(" #n ")" ::: "memory")
; #define PG8_WAIT_L(n) asm volatile("s_waitcnt lgkmcnt(" #n ")" ::: "memory")
; #define PG8_BAR __builtin_amdgcn_s_barrier()
; template <class Epi, class Sched, bool ALIGN_EPI = false, bool SP2 = false>
; __device__ __forceinline__ void gemm_phase(PG8_LAS unsigned char* lds, const Gemm g, const Sched& S, const Epi& E, const int tid_in) {
;     ...
;         for (int t = 0; t < nt; t += 2) {
;             const bool last = (t == nt - 2);
;             const char* a1 = cA + (size_t)(t + 1) * kstep;
;             const char* a2 = last ? nA : cA + (size_t)(t + 2) * kstep; const char* b2 = last ? nB : cB + (size_t)(t + 2) * kstep;
;             const char* a3 = a2 + kstep; const char* b3 = b2 + kstep;
;             if (last && has_next) S.a_ready(nxt);
;             if constexpr (SP2) {
;             PG8_LDB(B0, 0, 0); PG8_LDB(B1, 0, 1); PG8_SCHED; PG8_LDA(At, 0, 0); PG8_STAGE(PG8_SA(1, 1), a1 + hstep, voffA);
;             PG8_WAIT_V(8); PG8_WAIT_L(0); PG8_BAR; PG8_MMA(0, 0, At, B0); PG8_MMA(0, 1, At, B1); PG8_BAR; PG8_SCHED;
;             PG8_LDA(At, 0, 1); PG8_STAGE(PG8_SB(0, 0), b2, voffB); PG8_STAGE(PG8_SB(0, 1), b2 + hstep, voffB); PG8_STAGE(PG8_SA(0, 0), a2, voffA);
;             PG8_WAIT_V(8); PG8_WAIT_L(0); PG8_BAR; PG8_MMA(1, 0, At, B0); PG8_MMA(1, 1, At, B1); PG8_BAR; PG8_SCHED;
;             PG8_LDB(B0, 1, 0); PG8_LDB(B1, 1, 1); PG8_SCHED; PG8_LDA(At, 1, 0); PG8_STAGE(PG8_SA(0, 1), a2 + hstep, voffA);
;             PG8_WAIT_V(8); PG8_WAIT_L(0); PG8_BAR; PG8_MMA(0, 0, At, B0); PG8_MMA(0, 1, At, B1); PG8_BAR; PG8_SCHED;
;             PG8_LDA(At, 1, 1); PG8_STAGE(PG8_SB(1, 0), b3, voffB); PG8_STAGE(PG8_SB(1, 1), b3 + hstep, voffB); PG8_STAGE(PG8_SA(1, 0), a3, voffA);
;             PG8_WAIT_V(8); PG8_WAIT_L(0); PG8_BAR; PG8_MMA(1, 0, At, B0); PG8_MMA(1, 1, At, B1); PG8_BAR; PG8_SCHED;
	s_add_i32 s10, s61, s19
	v_lshl_add_u64 v[180:181], v[180:181], 0, s[2:3]
	s_mov_b32 m0, s10
	ds_read_b128 v[176:179], v198 offset:49152
	ds_read_b128 v[200:203], v198 offset:50176
	ds_read_b128 v[204:207], v198 offset:51200
	ds_read_b128 v[208:211], v198 offset:52224
	ds_read_b128 v[212:215], v198 offset:53248
	ds_read_b128 v[216:219], v198 offset:54272
	ds_read_b128 v[220:223], v198 offset:55296
	ds_read_b128 v[242:245], v198 offset:56320
	global_load_lds_dwordx4 v[180:181], off
	s_add_i32 m0, s10, 0x2000
	s_add_u32 s8, s8, 0x80080
	v_lshl_add_u64 v[180:181], v[184:185], 0, s[2:3]
	s_addc_u32 s9, s9, 0
	s_add_i32 s10, s62, s19
	global_load_lds_dwordx4 v[180:181], off
	v_lshl_add_u64 v[180:181], s[8:9], 0, v[164:165]
	s_mov_b32 m0, s10
	s_nop 0
	global_load_lds_dwordx4 v[180:181], off
	v_lshl_add_u64 v[180:181], s[8:9], 0, v[168:169]
	s_add_i32 m0, s10, 0x2000
	s_nop 0
	global_load_lds_dwordx4 v[180:181], off
	v_lshl_add_u64 v[180:181], v[186:187], 0, s[2:3]
	s_mov_b32 m0, s46
	s_nop 0
	global_load_lds_dwordx4 v[180:181], off
	v_lshl_add_u64 v[180:181], v[224:225], 0, s[2:3]
	s_mov_b32 m0, s49
	s_nop 0
	global_load_lds_dwordx4 v[180:181], off
	s_waitcnt vmcnt(8)
	s_waitcnt lgkmcnt(0)
	s_barrier
	s_setprio 1
	s_waitcnt lgkmcnt(0)
	v_mfma_f32_16x16x32_bf16 v[60:63], v[64:67], v[176:179], v[60:63]
	v_mfma_f32_16x16x32_bf16 v[56:59], v[88:91], v[176:179], v[56:59]
	v_mfma_f32_16x16x32_bf16 v[44:47], v[64:67], v[204:207], v[44:47]
	v_mfma_f32_16x16x32_bf16 v[40:43], v[88:91], v[204:207], v[40:43]
	v_mfma_f32_16x16x32_bf16 v[28:31], v[64:67], v[212:215], v[28:31]
	v_mfma_f32_16x16x32_bf16 v[24:27], v[88:91], v[212:215], v[24:27]
	v_mfma_f32_16x16x32_bf16 v[12:15], v[64:67], v[220:223], v[12:15]
	v_mfma_f32_16x16x32_bf16 v[8:11], v[88:91], v[220:223], v[8:11]
	v_mfma_f32_16x16x32_bf16 v[60:63], v[68:71], v[200:203], v[60:63]
	v_mfma_f32_16x16x32_bf16 v[56:59], v[92:95], v[200:203], v[56:59]
	v_mfma_f32_16x16x32_bf16 v[44:47], v[68:71], v[208:211], v[44:47]
	v_mfma_f32_16x16x32_bf16 v[40:43], v[92:95], v[208:211], v[40:43]
	v_mfma_f32_16x16x32_bf16 v[28:31], v[68:71], v[216:219], v[28:31]
	v_mfma_f32_16x16x32_bf16 v[24:27], v[92:95], v[216:219], v[24:27]
	v_mfma_f32_16x16x32_bf16 v[12:15], v[68:71], v[242:245], v[12:15]
	v_mfma_f32_16x16x32_bf16 v[8:11], v[92:95], v[242:245], v[8:11]
	s_setprio 0
	s_setprio 1
	v_mfma_f32_16x16x32_bf16 v[52:55], v[106:109], v[176:179], v[52:55]
	v_mfma_f32_16x16x32_bf16 v[48:51], v[130:133], v[176:179], v[48:51]
	v_mfma_f32_16x16x32_bf16 v[36:39], v[106:109], v[204:207], v[36:39]
	v_mfma_f32_16x16x32_bf16 v[32:35], v[130:133], v[204:207], v[32:35]
	v_mfma_f32_16x16x32_bf16 v[20:23], v[106:109], v[212:215], v[20:23]
	v_mfma_f32_16x16x32_bf16 v[16:19], v[130:133], v[212:215], v[16:19]
	v_mfma_f32_16x16x32_bf16 v[4:7], v[106:109], v[220:223], v[4:7]
	v_mfma_f32_16x16x32_bf16 v[0:3], v[130:133], v[220:223], v[0:3]
	v_mfma_f32_16x16x32_bf16 v[52:55], v[110:113], v[200:203], v[52:55]
	v_mfma_f32_16x16x32_bf16 v[48:51], v[134:137], v[200:203], v[48:51]
	v_mfma_f32_16x16x32_bf16 v[36:39], v[110:113], v[208:211], v[36:39]
	v_mfma_f32_16x16x32_bf16 v[32:35], v[134:137], v[208:211], v[32:35]
	v_mfma_f32_16x16x32_bf16 v[20:23], v[110:113], v[216:219], v[20:23]
	v_mfma_f32_16x16x32_bf16 v[16:19], v[134:137], v[216:219], v[16:19]
	v_mfma_f32_16x16x32_bf16 v[4:7], v[110:113], v[242:245], v[4:7]
	v_mfma_f32_16x16x32_bf16 v[0:3], v[134:137], v[242:245], v[0:3]
	s_setprio 0
	s_barrier
	s_add_i32 s57, s57, 2
	s_add_u32 s42, s42, 0x100
	s_addc_u32 s43, s43, 0
	s_add_u32 s45, s45, 0x100
	s_addc_u32 s55, s55, 0
	s_cmp_gt_u32 s57, 29
	s_cbranch_scc0 .LBB0_593
	s_and_b64 vcc, exec, s[50:51]
	s_cbranch_vccz .LBB0_596
	s_barrier
